# FFT stage matrices generated at the end of phase 2 by the workgroups without a third V unit instead of in phase 0
# baseline (speedup 1.0000x reference)
.LBB0_89:
	s_or_b64 exec, exec, s[0:1]
	s_cmp_eq_u32 s84, 0x100
	s_cbranch_scc1 .LBB0_118
	s_mov_b32 s0, 0x18000
	v_cmp_gt_i32_e32 vcc, s0, v0
	s_and_saveexec_b64 s[0:1], vcc
	s_cbranch_execz .LBB0_98
	s_add_u32 s2, s80, 0x280000
	s_addc_u32 s3, s81, 0
	s_lshl_b32 s6, s84, 9
	v_ashrrev_i32_e32 v1, 31, v0
	v_lshl_add_u64 v[2:3], v[0:1], 1, s[80:81]
	s_mov_b64 s[8:9], 0x240000
	s_ashr_i32 s7, s6, 31
	v_lshl_add_u64 v[2:3], v[2:3], 0, s[8:9]
	s_lshl_b64 s[8:9], s[6:7], 1
	s_mov_b64 s[10:11], 0
	s_mov_b32 s7, 0xffff
	s_movk_i32 s16, 0x4000
	v_mov_b32_e32 v5, 0
	s_mov_b32 s17, 0x8000
	s_mov_b32 s18, 0x17fff
	v_mov_b32_e32 v1, v0
	s_branch .LBB0_92

.LBB0_323:
	s_waitcnt vmcnt(0)
	s_barrier
	s_cmp_eq_u32 s84, 0x100
	s_cbranch_scc0 .Ltab_skip
	s_cmpk_lt_u32 s33, 0x80
	s_cbranch_scc1 .Ltab_skip
	s_mov_b64 s[98:99], s[0:1]
	s_sub_i32 s2, s33, 0x80
	s_lshl_b32 s2, s2, 9
	v_add_u32_e32 v0, s2, v164
	s_mov_b64 s[0:1], exec
.Ltab_89:
	s_or_b64 exec, exec, s[0:1]
	s_mov_b32 s0, 0x18000
	v_cmp_gt_i32_e32 vcc, s0, v0
	s_and_saveexec_b64 s[0:1], vcc
	s_cbranch_execz .Ltab_98
	s_add_u32 s2, s80, 0x280000
	s_addc_u32 s3, s81, 0
	s_mov_b32 s6, 0x10000
	v_ashrrev_i32_e32 v1, 31, v0
	v_lshl_add_u64 v[2:3], v[0:1], 1, s[80:81]
	s_mov_b64 s[8:9], 0x240000
	s_ashr_i32 s7, s6, 31
	v_lshl_add_u64 v[2:3], v[2:3], 0, s[8:9]
	s_lshl_b64 s[8:9], s[6:7], 1
	s_mov_b64 s[10:11], 0
	s_mov_b32 s7, 0xffff
	s_movk_i32 s16, 0x4000
	v_mov_b32_e32 v5, 0
	s_mov_b32 s17, 0x8000
	s_mov_b32 s18, 0x17fff
	v_mov_b32_e32 v1, v0
	s_branch .Ltab_92

.Ltab_98:
	s_or_b64 exec, exec, s[0:1]
	s_mov_b32 s0, 0xc0000
	v_cmp_gt_i32_e32 vcc, s0, v0
	s_and_saveexec_b64 s[6:7], vcc
	s_cbranch_execz .Ltab_117
	s_mov_b32 s12, 0x10000
	s_mov_b64 s[8:9], 0
	s_mov_b32 s13, 0x80000
	v_mov_b32_e32 v1, 0x1000
	v_mov_b32_e32 v6, 0x2000
	v_mov_b32_e32 v7, 0x2f800000
	v_mov_b32_e32 v8, 0x2f000000
	v_mov_b32_e32 v3, 0
	s_mov_b32 s14, 0xbffff
	s_branch .Ltab_101

.Ltab_117:
	s_or_b64 exec, exec, s[6:7]
	s_mov_b64 s[0:1], s[98:99]
.Ltab_skip:
.LBB0_324:
	s_cmp_gt_i32 s83, 3
	s_cselect_b64 s[2:3], -1, 0
	s_and_b64 s[0:1], s[0:1], s[2:3]
	s_andn2_b64 vcc, exec, s[0:1]
	s_cbranch_vccnz .LBB0_378
	s_waitcnt vmcnt(0)
	s_waitcnt vmcnt(0) lgkmcnt(0)
	s_barrier
	s_mov_b64 s[0:1], exec
	v_readlane_b32 s4, v252, 1
	v_readlane_b32 s5, v252, 2
	s_and_b64 s[4:5], s[0:1], s[4:5]
	s_mov_b64 exec, s[4:5]
	s_cbranch_execz .LBB0_377
	s_add_i32 s4, 0, 0x20100
	v_mov_b32_e32 v0, s4
	s_waitcnt vmcnt(0) expcnt(0) lgkmcnt(0)
	ds_read_b32 v2, v0
	s_add_i32 s4, 0, 0x20104
	v_mov_b32_e32 v0, s4
	ds_read_b32 v0, v0
	s_waitcnt lgkmcnt(1)
	v_cmp_ne_u32_e32 vcc, 0, v2
	s_cbranch_vccnz .LBB0_341
	v_readlane_b32 s4, v252, 0
	s_mul_i32 s38, s85, s4
	s_add_u32 s4, s80, 0xf0200
	s_addc_u32 s5, s81, 0
	s_add_u32 s6, s80, 0xf0400
	s_addc_u32 s7, s81, 0
	s_add_u32 s8, s80, 0xf0500
	s_addc_u32 s9, s81, 0
	s_add_u32 s10, s80, 0xf0600
	s_addc_u32 s11, s81, 0
	s_add_u32 s12, s80, 0xf0700
	s_addc_u32 s13, s81, 0
	s_add_u32 s14, s80, 0xf0800
	s_addc_u32 s15, s81, 0
	s_add_u32 s16, s80, 0xf0900
	s_addc_u32 s17, s81, 0
	s_add_u32 s18, s80, 0xf0a00
	s_addc_u32 s19, s81, 0
	s_add_u32 s20, s80, 0xf0b00
	s_addc_u32 s21, s81, 0
	s_add_u32 s22, s80, 0xf0c00
	s_addc_u32 s23, s81, 0
	s_add_u32 s24, s80, 0xf0d00
	s_addc_u32 s25, s81, 0
	s_add_u32 s26, s80, 0xf0e00
	s_addc_u32 s27, s81, 0
	s_add_u32 s28, s80, 0xf0f00
	s_addc_u32 s29, s81, 0
	s_add_u32 s30, s80, 0xf1000
	s_addc_u32 s31, s81, 0
	s_add_u32 s34, s80, 0xf1100
	s_addc_u32 s35, s81, 0
	s_add_u32 s36, s80, 0xf1200
	s_addc_u32 s37, s81, 0
	s_add_u32 s44, s80, 0xf1300
	s_mul_i32 s38, s38, s84
	s_addc_u32 s45, s81, 0
	s_mov_b32 s39, 1
	v_mov_b32_e32 v16, 0
	s_branch .LBB0_329
